# mixers work queue: prompt-DSA items and stick units interleaved 2:1 (remap of the dequeued index), short units still last
# baseline (speedup 1.0000x reference)
.LBB0_528:
	s_or_b64 exec, exec, s[0:1]
	s_waitcnt lgkmcnt(0)
	s_barrier
	ds_read_b32 v0, v200
	s_waitcnt lgkmcnt(0)
	v_readfirstlane_b32 s78, v0
	s_cmpk_gt_i32 s78, 0x1aff
	s_cbranch_scc1 .LBB0_1978
	s_cmp_lt_u32 s78, 64
	s_cbranch_scc1 .Lq_doneA
	s_sub_i32 s0, s78, 64
	s_cmp_lt_u32 s0, 0x1800
	s_cbranch_scc0 .Lq_doneA
	s_mul_i32 s1, s0, 0xaaab
	s_lshr_b32 s1, s1, 17
	s_mul_i32 s2, s1, 3
	s_sub_i32 s2, s0, s2
	s_cmp_lt_u32 s2, 2
	s_cbranch_scc0 .Lq_otherA
	s_lshl_b32 s1, s1, 1
	s_add_i32 s1, s1, s2
	s_add_i32 s78, s1, 64
	s_branch .Lq_doneA
.Lq_otherA:
	s_add_i32 s78, s1, 0x1040
.Lq_doneA:
	v_readlane_b32 s0, v249, 52
	v_readlane_b32 s1, v249, 53
	s_lshl_b32 s4, s0, 9
	s_mov_b32 s5, s73
	v_writelane_b32 v250, s4, 18
	s_lshl_b32 s1, s0, 8
	s_ashr_i32 s2, s6, 6
	v_writelane_b32 v250, s5, 19
	s_or_b32 s4, s1, 0xfffff800
	v_writelane_b32 v250, s4, 20
	s_lshl_b32 s4, s0, 2
	v_writelane_b32 v250, s4, 21
	s_lshl_b32 s4, s0, 16
	v_writelane_b32 v250, s4, 22
	s_mul_i32 s3, s2, 0x4500
	v_writelane_b32 v250, s2, 23
	s_addk_i32 s2, 0x4000
	v_writelane_b32 v250, s2, 24
	s_lshl_b32 s0, s0, 4
	v_writelane_b32 v250, s0, 25
	v_writelane_b32 v250, s1, 26
	s_or_b32 s0, s1, 0xfffff000
	v_writelane_b32 v250, s0, 27
	s_add_i32 s0, s3, 0x4100
	v_writelane_b32 v250, s0, 28
	s_add_i32 s0, s3, 0x4200
	v_writelane_b32 v250, s0, 29
	s_add_i32 s0, s3, 0x400
	v_writelane_b32 v250, s0, 30
	s_add_i32 s0, s3, 0x1400
	v_writelane_b32 v250, s0, 31
	s_add_i32 s0, s3, 0x4180
	v_writelane_b32 v250, s0, 32
	s_add_i32 s0, s3, 0x200
	v_writelane_b32 v250, s0, 33
	v_writelane_b32 v250, s3, 34
	s_add_i32 s0, s3, 0x1200
	v_writelane_b32 v250, s0, 35
	s_branch .LBB0_531
.LBB0_530:
	s_or_b64 exec, exec, s[0:1]
	s_waitcnt lgkmcnt(0)
	s_barrier
	ds_read_b32 v0, v200
	s_waitcnt lgkmcnt(0)
	v_readfirstlane_b32 s78, v0
	s_cmpk_lt_i32 s78, 0x1b00
	s_cbranch_scc0 .LBB0_1977
	s_cmp_lt_u32 s78, 64
	s_cbranch_scc1 .Lq_doneB
	s_sub_i32 s0, s78, 64
	s_cmp_lt_u32 s0, 0x1800
	s_cbranch_scc0 .Lq_doneB
	s_mul_i32 s1, s0, 0xaaab
	s_lshr_b32 s1, s1, 17
	s_mul_i32 s2, s1, 3
	s_sub_i32 s2, s0, s2
	s_cmp_lt_u32 s2, 2
	s_cbranch_scc0 .Lq_otherB
	s_lshl_b32 s1, s1, 1
	s_add_i32 s1, s1, s2
	s_add_i32 s78, s1, 64
	s_branch .Lq_doneB

.Lq_doneB:
.LBB0_531:
	v_mov_b32_e32 v205, 0
	s_mov_b64 s[0:1], exec
	v_readlane_b32 s2, v250, 16
	v_readlane_b32 s3, v250, 17
	s_and_b64 s[2:3], s[0:1], s[2:3]
	s_mov_b64 exec, s[2:3]
	s_cbranch_execz .LBB0_535
	v_readlane_b32 s4, v250, 14
	v_readlane_b32 s5, v250, 15
	v_mov_b32_e32 v205, 1
	s_nop 4
	global_atomic_add v205, v1, v205, s[4:5] sc0
